# out-proj epilogue: 16-lane row sum-of-squares butterfly via v_mov_b32_dpp (quad_perm / row_half_mirror / row_mirror) instead of 4 serial ds_bpermute round trips; f32 adds unchanged
# speedup vs baseline: 1.0370x; 1.0075x over previous
; DI float bflo(unsigned v) { return __uint_as_float(v << 16); }
; DI float bfhi(unsigned v) { return __uint_as_float(v & 0xffff0000u); }
; template <int EPI>
; DI void gemm_tile(const Params& p, int layer, int mt, int nt, u16* sm, int wv) {
;     ...
;       for (int t = 0; t < 16; ++t) {
;         const int row = (lane >> 4) + 4 * t;
;         const f32x4 a4 = *(const f32x4*)(stg + row * 68 + kc * 4);
;         const float v0 = bflo(xb[t][0]) + a4[0], v1 = bfhi(xb[t][0]) + a4[1], v2 = bflo(xb[t][1]) + a4[2], v3 = bfhi(xb[t][1]) + a4[3];
;         float sq = v0 * v0 + v1 * v1 + v2 * v2 + v3 * v3;
;         u32x2 pv = {pk2(v0, v1), pk2(v2, v3)};
;         if (has_next) *(u32x2*)(xrow + (size_t)row * DM) = pv;
;         else *(u32x2*)(x2row + (size_t)row * DM) = pv;
;         sq += shx(sq, lane, 1); sq += shx(sq, lane, 2); sq += shx(sq, lane, 4); sq += shx(sq, lane, 8);
;         if (kc == 0) atomicAdd(ssn + mrow0 + row, sq);
.LBB0_403:
	v_and_b32_e32 v66, 63, v185
	v_lshlrev_b32_e32 v71, 2, v66
	v_pk_mul_f32 v[66:67], v[104:105], v[104:105]
	v_pk_mul_f32 v[104:105], v[136:137], v[136:137]
	v_add_f32_e32 v66, v66, v67
	v_add_f32_e32 v66, v104, v66
	v_xor_b32_e32 v138, 4, v71
	v_add_f32_e32 v66, v105, v66
	s_nop 1
	v_mov_b32_dpp v67, v66 quad_perm:[1,0,3,2] row_mask:0xf bank_mask:0xf
	v_xor_b32_e32 v137, 8, v71
	v_xor_b32_e32 v139, 16, v71
	v_xor_b32_e32 v136, 32, v71
	v_cmp_eq_u32_e64 s[36:37], 0, v180
	s_waitcnt lgkmcnt(0)
	v_add_f32_e32 v66, v66, v67
	s_nop 1
	v_mov_b32_dpp v67, v66 quad_perm:[2,3,0,1] row_mask:0xf bank_mask:0xf
	v_lshl_add_u64 v[104:105], v[68:69], 2, s[0:1]
	s_waitcnt lgkmcnt(0)
	v_add_f32_e32 v66, v66, v67
	s_nop 1
	v_mov_b32_dpp v67, v66 row_half_mirror row_mask:0xf bank_mask:0xf
	s_waitcnt lgkmcnt(0)
	v_add_f32_e32 v67, v66, v67
	s_nop 1
	v_mov_b32_dpp v71, v67 row_mirror row_mask:0xf bank_mask:0xf
	v_lshlrev_b32_e32 v66, 2, v183
	s_and_saveexec_b64 s[4:5], s[36:37]
	s_cbranch_execz .LBB0_405
	s_waitcnt lgkmcnt(0)
	v_add_f32_e32 v69, v67, v71
	v_mov_b32_e32 v67, v1
	v_lshl_add_u64 v[140:141], v[104:105], 0, v[66:67]
	global_atomic_add_f32 v[140:141], v69, off
.LBB0_405:
	s_or_b64 exec, exec, s[4:5]
	v_mul_u32_u24_e32 v67, 0x110, v183
	v_add_u32_e32 v69, v67, v184
	ds_read_b128 v[140:143], v69 offset:1088
	v_lshlrev_b32_e32 v144, 16, v132
	v_and_b32_e32 v145, 0xffff0000, v132
	v_lshlrev_b32_e32 v132, 16, v133
	v_and_b32_e32 v133, 0xffff0000, v133
	s_waitcnt lgkmcnt(0)
	v_pk_add_f32 v[140:141], v[140:141], v[144:145]
	v_pk_add_f32 v[142:143], v[142:143], v[132:133]
	v_pk_mul_f32 v[132:133], v[140:141], v[140:141]
	v_pk_mul_f32 v[144:145], v[142:143], v[142:143]
	v_add_f32_e32 v67, v132, v133
	v_add_f32_e32 v67, v144, v67
	v_add_f32_e32 v67, v145, v67
	s_nop 1
	v_mov_b32_dpp v71, v67 quad_perm:[1,0,3,2] row_mask:0xf bank_mask:0xf
	v_or_b32_e32 v132, 4, v183
	v_cndmask_b32_e64 v111, v135, v111, s[34:35]
	v_cndmask_b32_e64 v110, v134, v110, s[34:35]
	v_lshlrev_b32_e32 v134, 11, v132
	s_waitcnt lgkmcnt(0)
	v_add_f32_e32 v67, v67, v71
	s_nop 1
	v_mov_b32_dpp v71, v67 quad_perm:[2,3,0,1] row_mask:0xf bank_mask:0xf
	v_mov_b32_e32 v135, v1
	v_cvt_pk_bf16_f32 v140, v140, v141
	v_cvt_pk_bf16_f32 v141, v142, v143
	v_lshl_add_u64 v[134:135], v[110:111], 0, v[134:135]
	s_waitcnt lgkmcnt(0)
	v_add_f32_e32 v67, v67, v71
	s_nop 1
	v_mov_b32_dpp v71, v67 row_half_mirror row_mask:0xf bank_mask:0xf
	global_store_dwordx2 v[134:135], v[140:141], off
	s_waitcnt lgkmcnt(0)
	v_add_f32_e32 v67, v67, v71
	s_nop 1
	v_mov_b32_dpp v71, v67 row_mirror row_mask:0xf bank_mask:0xf
	s_and_saveexec_b64 s[4:5], s[36:37]
	s_cbranch_execz .LBB0_407
	s_waitcnt lgkmcnt(0)
	v_add_f32_e32 v71, v67, v71
	v_mov_b32_e32 v67, v1
	v_lshl_add_u64 v[134:135], v[104:105], 0, v[66:67]
	global_atomic_add_f32 v[134:135], v71, off offset:16
.LBB0_407:
	s_or_b64 exec, exec, s[4:5]
	ds_read_b128 v[140:143], v69 offset:2176
	v_lshlrev_b32_e32 v134, 16, v130
	v_and_b32_e32 v135, 0xffff0000, v130
	v_lshlrev_b32_e32 v130, 16, v131
	v_and_b32_e32 v131, 0xffff0000, v131
	s_waitcnt lgkmcnt(0)
	v_pk_add_f32 v[134:135], v[140:141], v[134:135]
	v_pk_add_f32 v[140:141], v[142:143], v[130:131]
	v_pk_mul_f32 v[130:131], v[134:135], v[134:135]
	v_pk_mul_f32 v[142:143], v[140:141], v[140:141]
	v_add_f32_e32 v67, v130, v131
	v_add_f32_e32 v67, v142, v67
	v_add_f32_e32 v67, v143, v67
	s_nop 1
	v_mov_b32_dpp v71, v67 quad_perm:[1,0,3,2] row_mask:0xf bank_mask:0xf
	v_or_b32_e32 v130, 8, v183
	v_cvt_pk_bf16_f32 v134, v134, v135
	v_cvt_pk_bf16_f32 v135, v140, v141
	v_lshlrev_b32_e32 v140, 11, v130
	s_waitcnt lgkmcnt(0)
	v_add_f32_e32 v67, v67, v71
	s_nop 1
	v_mov_b32_dpp v71, v67 quad_perm:[2,3,0,1] row_mask:0xf bank_mask:0xf
	v_mov_b32_e32 v141, v1
	v_lshl_add_u64 v[140:141], v[110:111], 0, v[140:141]
	global_store_dwordx2 v[140:141], v[134:135], off
	s_waitcnt lgkmcnt(0)
	v_add_f32_e32 v67, v67, v71
	s_nop 1
	v_mov_b32_dpp v71, v67 row_half_mirror row_mask:0xf bank_mask:0xf
	s_waitcnt lgkmcnt(0)
	v_add_f32_e32 v67, v67, v71
	s_nop 1
	v_mov_b32_dpp v71, v67 row_mirror row_mask:0xf bank_mask:0xf
	s_and_saveexec_b64 s[4:5], s[36:37]
	s_cbranch_execz .LBB0_409
	s_waitcnt lgkmcnt(0)
	v_add_f32_e32 v71, v67, v71
	v_mov_b32_e32 v67, v1
	v_lshl_add_u64 v[134:135], v[104:105], 0, v[66:67]
	global_atomic_add_f32 v[134:135], v71, off offset:32
.LBB0_409:
	s_or_b64 exec, exec, s[4:5]
	ds_read_b128 v[140:143], v69 offset:3264
	v_lshlrev_b32_e32 v134, 16, v128
	v_and_b32_e32 v135, 0xffff0000, v128
	v_lshlrev_b32_e32 v128, 16, v129
	v_and_b32_e32 v129, 0xffff0000, v129
	s_waitcnt lgkmcnt(0)
	v_pk_add_f32 v[134:135], v[140:141], v[134:135]
	v_pk_add_f32 v[140:141], v[142:143], v[128:129]
	v_pk_mul_f32 v[128:129], v[134:135], v[134:135]
	v_pk_mul_f32 v[142:143], v[140:141], v[140:141]
	v_add_f32_e32 v67, v128, v129
	v_add_f32_e32 v67, v142, v67
	v_add_f32_e32 v67, v143, v67
	s_nop 1
	v_mov_b32_dpp v71, v67 quad_perm:[1,0,3,2] row_mask:0xf bank_mask:0xf
	v_or_b32_e32 v128, 12, v183
	v_cvt_pk_bf16_f32 v134, v134, v135
	v_cvt_pk_bf16_f32 v135, v140, v141
	v_lshlrev_b32_e32 v140, 11, v128
	s_waitcnt lgkmcnt(0)
	v_add_f32_e32 v67, v67, v71
	s_nop 1
	v_mov_b32_dpp v71, v67 quad_perm:[2,3,0,1] row_mask:0xf bank_mask:0xf
	v_mov_b32_e32 v141, v1
	v_lshl_add_u64 v[140:141], v[110:111], 0, v[140:141]
	global_store_dwordx2 v[140:141], v[134:135], off
	s_waitcnt lgkmcnt(0)
	v_add_f32_e32 v67, v67, v71
	s_nop 1
	v_mov_b32_dpp v71, v67 row_half_mirror row_mask:0xf bank_mask:0xf
	s_waitcnt lgkmcnt(0)
	v_add_f32_e32 v67, v67, v71
	s_nop 1
	v_mov_b32_dpp v71, v67 row_mirror row_mask:0xf bank_mask:0xf
	s_and_saveexec_b64 s[4:5], s[36:37]
	s_cbranch_execz .LBB0_411
	s_waitcnt lgkmcnt(0)
	v_add_f32_e32 v71, v67, v71
	v_mov_b32_e32 v67, v1
	v_lshl_add_u64 v[134:135], v[104:105], 0, v[66:67]
	global_atomic_add_f32 v[134:135], v71, off offset:48
; DI float bflo(unsigned v) { return __uint_as_float(v << 16); }
; DI float bfhi(unsigned v) { return __uint_as_float(v & 0xffff0000u); }
; template <int EPI>
; DI void gemm_tile(const Params& p, int layer, int mt, int nt, u16* sm, int wv) {
;     ...
;       for (int t = 0; t < 16; ++t) {
;         const int row = (lane >> 4) + 4 * t;
;         const f32x4 a4 = *(const f32x4*)(stg + row * 68 + kc * 4);
;         const float v0 = bflo(xb[t][0]) + a4[0], v1 = bfhi(xb[t][0]) + a4[1], v2 = bflo(xb[t][1]) + a4[2], v3 = bfhi(xb[t][1]) + a4[3];
;         float sq = v0 * v0 + v1 * v1 + v2 * v2 + v3 * v3;
;         u32x2 pv = {pk2(v0, v1), pk2(v2, v3)};
;         if (has_next) *(u32x2*)(xrow + (size_t)row * DM) = pv;
;         else *(u32x2*)(x2row + (size_t)row * DM) = pv;
;         sq += shx(sq, lane, 1); sq += shx(sq, lane, 2); sq += shx(sq, lane, 4); sq += shx(sq, lane, 8);
;         if (kc == 0) atomicAdd(ssn + mrow0 + row, sq);
.LBB0_411:
	s_or_b64 exec, exec, s[4:5]
	ds_read_b128 v[140:143], v69 offset:4352
	v_lshlrev_b32_e32 v134, 16, v126
	v_and_b32_e32 v135, 0xffff0000, v126
	v_lshlrev_b32_e32 v126, 16, v127
	v_and_b32_e32 v127, 0xffff0000, v127
	s_waitcnt lgkmcnt(0)
	v_pk_add_f32 v[134:135], v[140:141], v[134:135]
	v_pk_add_f32 v[140:141], v[142:143], v[126:127]
	v_pk_mul_f32 v[126:127], v[134:135], v[134:135]
	v_pk_mul_f32 v[142:143], v[140:141], v[140:141]
	v_add_f32_e32 v67, v126, v127
	v_add_f32_e32 v67, v142, v67
	v_add_f32_e32 v67, v143, v67
	s_nop 1
	v_mov_b32_dpp v71, v67 quad_perm:[1,0,3,2] row_mask:0xf bank_mask:0xf
	v_or_b32_e32 v126, 16, v183
	v_cvt_pk_bf16_f32 v134, v134, v135
	v_cvt_pk_bf16_f32 v135, v140, v141
	v_lshlrev_b32_e32 v140, 11, v126
	s_waitcnt lgkmcnt(0)
	v_add_f32_e32 v67, v67, v71
	s_nop 1
	v_mov_b32_dpp v71, v67 quad_perm:[2,3,0,1] row_mask:0xf bank_mask:0xf
	v_mov_b32_e32 v141, v1
	v_lshl_add_u64 v[140:141], v[110:111], 0, v[140:141]
	global_store_dwordx2 v[140:141], v[134:135], off
	s_waitcnt lgkmcnt(0)
	v_add_f32_e32 v67, v67, v71
	s_nop 1
	v_mov_b32_dpp v71, v67 row_half_mirror row_mask:0xf bank_mask:0xf
	s_waitcnt lgkmcnt(0)
	v_add_f32_e32 v67, v67, v71
	s_nop 1
	v_mov_b32_dpp v71, v67 row_mirror row_mask:0xf bank_mask:0xf
	s_and_saveexec_b64 s[4:5], s[36:37]
	s_cbranch_execz .LBB0_413
	s_waitcnt lgkmcnt(0)
	v_add_f32_e32 v71, v67, v71
	v_mov_b32_e32 v67, v1
	v_lshl_add_u64 v[134:135], v[104:105], 0, v[66:67]
	global_atomic_add_f32 v[134:135], v71, off offset:64
.LBB0_413:
	s_or_b64 exec, exec, s[4:5]
	ds_read_b128 v[140:143], v69 offset:5440
	v_lshlrev_b32_e32 v134, 16, v124
	v_and_b32_e32 v135, 0xffff0000, v124
	v_lshlrev_b32_e32 v124, 16, v125
	v_and_b32_e32 v125, 0xffff0000, v125
	s_waitcnt lgkmcnt(0)
	v_pk_add_f32 v[134:135], v[140:141], v[134:135]
	v_pk_add_f32 v[140:141], v[142:143], v[124:125]
	v_pk_mul_f32 v[124:125], v[134:135], v[134:135]
	v_pk_mul_f32 v[142:143], v[140:141], v[140:141]
	v_add_f32_e32 v67, v124, v125
	v_add_f32_e32 v67, v142, v67
	v_add_f32_e32 v67, v143, v67
	s_nop 1
	v_mov_b32_dpp v71, v67 quad_perm:[1,0,3,2] row_mask:0xf bank_mask:0xf
	v_or_b32_e32 v124, 20, v183
	v_cvt_pk_bf16_f32 v134, v134, v135
	v_cvt_pk_bf16_f32 v135, v140, v141
	v_lshlrev_b32_e32 v140, 11, v124
	s_waitcnt lgkmcnt(0)
	v_add_f32_e32 v67, v67, v71
	s_nop 1
	v_mov_b32_dpp v71, v67 quad_perm:[2,3,0,1] row_mask:0xf bank_mask:0xf
	v_mov_b32_e32 v141, v1
	v_lshl_add_u64 v[140:141], v[110:111], 0, v[140:141]
	global_store_dwordx2 v[140:141], v[134:135], off
	s_waitcnt lgkmcnt(0)
	v_add_f32_e32 v67, v67, v71
	s_nop 1
	v_mov_b32_dpp v71, v67 row_half_mirror row_mask:0xf bank_mask:0xf
	s_waitcnt lgkmcnt(0)
	v_add_f32_e32 v67, v67, v71
	s_nop 1
	v_mov_b32_dpp v71, v67 row_mirror row_mask:0xf bank_mask:0xf
	s_and_saveexec_b64 s[4:5], s[36:37]
	s_cbranch_execz .LBB0_415
	s_waitcnt lgkmcnt(0)
	v_add_f32_e32 v71, v67, v71
	v_mov_b32_e32 v67, v1
	v_lshl_add_u64 v[134:135], v[104:105], 0, v[66:67]
	global_atomic_add_f32 v[134:135], v71, off offset:80
.LBB0_415:
	s_or_b64 exec, exec, s[4:5]
	ds_read_b128 v[140:143], v69 offset:6528
	v_lshlrev_b32_e32 v134, 16, v122
	v_and_b32_e32 v135, 0xffff0000, v122
	v_lshlrev_b32_e32 v122, 16, v123
	v_and_b32_e32 v123, 0xffff0000, v123
	s_waitcnt lgkmcnt(0)
	v_pk_add_f32 v[134:135], v[140:141], v[134:135]
	v_pk_add_f32 v[140:141], v[142:143], v[122:123]
	v_pk_mul_f32 v[122:123], v[134:135], v[134:135]
	v_pk_mul_f32 v[142:143], v[140:141], v[140:141]
	v_add_f32_e32 v67, v122, v123
	v_add_f32_e32 v67, v142, v67
	v_add_f32_e32 v67, v143, v67
	s_nop 1
	v_mov_b32_dpp v71, v67 quad_perm:[1,0,3,2] row_mask:0xf bank_mask:0xf
	v_or_b32_e32 v122, 24, v183
	v_cvt_pk_bf16_f32 v134, v134, v135
	v_cvt_pk_bf16_f32 v135, v140, v141
	v_lshlrev_b32_e32 v140, 11, v122
	s_waitcnt lgkmcnt(0)
	v_add_f32_e32 v67, v67, v71
	s_nop 1
	v_mov_b32_dpp v71, v67 quad_perm:[2,3,0,1] row_mask:0xf bank_mask:0xf
	v_mov_b32_e32 v141, v1
	v_lshl_add_u64 v[140:141], v[110:111], 0, v[140:141]
	global_store_dwordx2 v[140:141], v[134:135], off
	s_waitcnt lgkmcnt(0)
	v_add_f32_e32 v67, v67, v71
	s_nop 1
	v_mov_b32_dpp v71, v67 row_half_mirror row_mask:0xf bank_mask:0xf
	s_waitcnt lgkmcnt(0)
	v_add_f32_e32 v67, v67, v71
	s_nop 1
	v_mov_b32_dpp v71, v67 row_mirror row_mask:0xf bank_mask:0xf
	s_and_saveexec_b64 s[4:5], s[36:37]
	s_cbranch_execz .LBB0_417
	s_waitcnt lgkmcnt(0)
	v_add_f32_e32 v71, v67, v71
	v_mov_b32_e32 v67, v1
	v_lshl_add_u64 v[134:135], v[104:105], 0, v[66:67]
	global_atomic_add_f32 v[134:135], v71, off offset:96
.LBB0_417:
	s_or_b64 exec, exec, s[4:5]
	ds_read_b128 v[140:143], v69 offset:7616
	v_lshlrev_b32_e32 v134, 16, v120
	v_and_b32_e32 v135, 0xffff0000, v120
	v_lshlrev_b32_e32 v120, 16, v121
	v_and_b32_e32 v121, 0xffff0000, v121
	s_waitcnt lgkmcnt(0)
	v_pk_add_f32 v[134:135], v[140:141], v[134:135]
	v_pk_add_f32 v[140:141], v[142:143], v[120:121]
	v_pk_mul_f32 v[120:121], v[134:135], v[134:135]
	v_pk_mul_f32 v[142:143], v[140:141], v[140:141]
	v_add_f32_e32 v67, v120, v121
	v_add_f32_e32 v67, v142, v67
	v_add_f32_e32 v67, v143, v67
	s_nop 1
	v_mov_b32_dpp v71, v67 quad_perm:[1,0,3,2] row_mask:0xf bank_mask:0xf
	v_or_b32_e32 v120, 28, v183
	v_cvt_pk_bf16_f32 v134, v134, v135
	v_cvt_pk_bf16_f32 v135, v140, v141
	v_lshlrev_b32_e32 v140, 11, v120
	s_waitcnt lgkmcnt(0)
	v_add_f32_e32 v67, v67, v71
	s_nop 1
	v_mov_b32_dpp v71, v67 quad_perm:[2,3,0,1] row_mask:0xf bank_mask:0xf
	v_mov_b32_e32 v141, v1
	v_lshl_add_u64 v[140:141], v[110:111], 0, v[140:141]
	global_store_dwordx2 v[140:141], v[134:135], off
	s_waitcnt lgkmcnt(0)
	v_add_f32_e32 v67, v67, v71
	s_nop 1
	v_mov_b32_dpp v71, v67 row_half_mirror row_mask:0xf bank_mask:0xf
	s_waitcnt lgkmcnt(0)
	v_add_f32_e32 v67, v67, v71
	s_nop 1
	v_mov_b32_dpp v71, v67 row_mirror row_mask:0xf bank_mask:0xf
	s_and_saveexec_b64 s[4:5], s[36:37]
	s_cbranch_execz .LBB0_419
	s_waitcnt lgkmcnt(0)
	v_add_f32_e32 v71, v67, v71
	v_mov_b32_e32 v67, v1
	v_lshl_add_u64 v[134:135], v[104:105], 0, v[66:67]
	global_atomic_add_f32 v[134:135], v71, off offset:112
; DI float bflo(unsigned v) { return __uint_as_float(v << 16); }
; DI float bfhi(unsigned v) { return __uint_as_float(v & 0xffff0000u); }
; template <int EPI>
; DI void gemm_tile(const Params& p, int layer, int mt, int nt, u16* sm, int wv) {
;     ...
;       for (int t = 0; t < 16; ++t) {
;         const int row = (lane >> 4) + 4 * t;
;         const f32x4 a4 = *(const f32x4*)(stg + row * 68 + kc * 4);
;         const float v0 = bflo(xb[t][0]) + a4[0], v1 = bfhi(xb[t][0]) + a4[1], v2 = bflo(xb[t][1]) + a4[2], v3 = bfhi(xb[t][1]) + a4[3];
;         float sq = v0 * v0 + v1 * v1 + v2 * v2 + v3 * v3;
;         u32x2 pv = {pk2(v0, v1), pk2(v2, v3)};
;         if (has_next) *(u32x2*)(xrow + (size_t)row * DM) = pv;
;         else *(u32x2*)(x2row + (size_t)row * DM) = pv;
;         sq += shx(sq, lane, 1); sq += shx(sq, lane, 2); sq += shx(sq, lane, 4); sq += shx(sq, lane, 8);
;         if (kc == 0) atomicAdd(ssn + mrow0 + row, sq);
.LBB0_419:
	s_or_b64 exec, exec, s[4:5]
	ds_read_b128 v[140:143], v69 offset:8704
	v_lshlrev_b32_e32 v134, 16, v118
	v_and_b32_e32 v135, 0xffff0000, v118
	v_lshlrev_b32_e32 v118, 16, v119
	v_and_b32_e32 v119, 0xffff0000, v119
	s_waitcnt lgkmcnt(0)
	v_pk_add_f32 v[134:135], v[140:141], v[134:135]
	v_pk_add_f32 v[140:141], v[142:143], v[118:119]
	v_pk_mul_f32 v[118:119], v[134:135], v[134:135]
	v_pk_mul_f32 v[142:143], v[140:141], v[140:141]
	v_add_f32_e32 v67, v118, v119
	v_add_f32_e32 v67, v142, v67
	v_add_f32_e32 v67, v143, v67
	s_nop 1
	v_mov_b32_dpp v71, v67 quad_perm:[1,0,3,2] row_mask:0xf bank_mask:0xf
	v_or_b32_e32 v118, 32, v183
	v_cvt_pk_bf16_f32 v134, v134, v135
	v_cvt_pk_bf16_f32 v135, v140, v141
	v_lshlrev_b32_e32 v140, 11, v118
	s_waitcnt lgkmcnt(0)
	v_add_f32_e32 v67, v67, v71
	s_nop 1
	v_mov_b32_dpp v71, v67 quad_perm:[2,3,0,1] row_mask:0xf bank_mask:0xf
	v_mov_b32_e32 v141, v1
	v_lshl_add_u64 v[140:141], v[110:111], 0, v[140:141]
	global_store_dwordx2 v[140:141], v[134:135], off
	s_waitcnt lgkmcnt(0)
	v_add_f32_e32 v67, v67, v71
	s_nop 1
	v_mov_b32_dpp v71, v67 row_half_mirror row_mask:0xf bank_mask:0xf
	s_waitcnt lgkmcnt(0)
	v_add_f32_e32 v67, v67, v71
	s_nop 1
	v_mov_b32_dpp v71, v67 row_mirror row_mask:0xf bank_mask:0xf
	s_and_saveexec_b64 s[4:5], s[36:37]
	s_cbranch_execz .LBB0_421
	s_waitcnt lgkmcnt(0)
	v_add_f32_e32 v71, v67, v71
	v_mov_b32_e32 v67, v1
	v_lshl_add_u64 v[134:135], v[104:105], 0, v[66:67]
	global_atomic_add_f32 v[134:135], v71, off offset:128
.LBB0_421:
	s_or_b64 exec, exec, s[4:5]
	ds_read_b128 v[140:143], v69 offset:9792
	v_lshlrev_b32_e32 v134, 16, v116
	v_and_b32_e32 v135, 0xffff0000, v116
	v_lshlrev_b32_e32 v116, 16, v117
	v_and_b32_e32 v117, 0xffff0000, v117
	s_waitcnt lgkmcnt(0)
	v_pk_add_f32 v[134:135], v[140:141], v[134:135]
	v_pk_add_f32 v[140:141], v[142:143], v[116:117]
	v_pk_mul_f32 v[116:117], v[134:135], v[134:135]
	v_pk_mul_f32 v[142:143], v[140:141], v[140:141]
	v_add_f32_e32 v67, v116, v117
	v_add_f32_e32 v67, v142, v67
	v_add_f32_e32 v67, v143, v67
	s_nop 1
	v_mov_b32_dpp v71, v67 quad_perm:[1,0,3,2] row_mask:0xf bank_mask:0xf
	v_or_b32_e32 v116, 36, v183
	v_cvt_pk_bf16_f32 v134, v134, v135
	v_cvt_pk_bf16_f32 v135, v140, v141
	v_lshlrev_b32_e32 v140, 11, v116
	s_waitcnt lgkmcnt(0)
	v_add_f32_e32 v67, v67, v71
	s_nop 1
	v_mov_b32_dpp v71, v67 quad_perm:[2,3,0,1] row_mask:0xf bank_mask:0xf
	v_mov_b32_e32 v141, v1
	v_lshl_add_u64 v[140:141], v[110:111], 0, v[140:141]
	global_store_dwordx2 v[140:141], v[134:135], off
	s_waitcnt lgkmcnt(0)
	v_add_f32_e32 v67, v67, v71
	s_nop 1
	v_mov_b32_dpp v71, v67 row_half_mirror row_mask:0xf bank_mask:0xf
	s_waitcnt lgkmcnt(0)
	v_add_f32_e32 v67, v67, v71
	s_nop 1
	v_mov_b32_dpp v71, v67 row_mirror row_mask:0xf bank_mask:0xf
	s_and_saveexec_b64 s[4:5], s[36:37]
	s_cbranch_execz .LBB0_423
	s_waitcnt lgkmcnt(0)
	v_add_f32_e32 v71, v67, v71
	v_mov_b32_e32 v67, v1
	v_lshl_add_u64 v[134:135], v[104:105], 0, v[66:67]
	global_atomic_add_f32 v[134:135], v71, off offset:144
.LBB0_423:
	s_or_b64 exec, exec, s[4:5]
	ds_read_b128 v[140:143], v69 offset:10880
	v_lshlrev_b32_e32 v134, 16, v114
	v_and_b32_e32 v135, 0xffff0000, v114
	v_lshlrev_b32_e32 v114, 16, v115
	v_and_b32_e32 v115, 0xffff0000, v115
	s_waitcnt lgkmcnt(0)
	v_pk_add_f32 v[134:135], v[140:141], v[134:135]
	v_pk_add_f32 v[140:141], v[142:143], v[114:115]
	v_pk_mul_f32 v[114:115], v[134:135], v[134:135]
	v_pk_mul_f32 v[142:143], v[140:141], v[140:141]
	v_add_f32_e32 v67, v114, v115
	v_add_f32_e32 v67, v142, v67
	v_add_f32_e32 v67, v143, v67
	s_nop 1
	v_mov_b32_dpp v71, v67 quad_perm:[1,0,3,2] row_mask:0xf bank_mask:0xf
	v_or_b32_e32 v114, 40, v183
	v_cvt_pk_bf16_f32 v134, v134, v135
	v_cvt_pk_bf16_f32 v135, v140, v141
	v_lshlrev_b32_e32 v140, 11, v114
	s_waitcnt lgkmcnt(0)
	v_add_f32_e32 v67, v67, v71
	s_nop 1
	v_mov_b32_dpp v71, v67 quad_perm:[2,3,0,1] row_mask:0xf bank_mask:0xf
	v_mov_b32_e32 v141, v1
	v_lshl_add_u64 v[140:141], v[110:111], 0, v[140:141]
	global_store_dwordx2 v[140:141], v[134:135], off
	s_waitcnt lgkmcnt(0)
	v_add_f32_e32 v67, v67, v71
	s_nop 1
	v_mov_b32_dpp v71, v67 row_half_mirror row_mask:0xf bank_mask:0xf
	s_waitcnt lgkmcnt(0)
	v_add_f32_e32 v67, v67, v71
	s_nop 1
	v_mov_b32_dpp v71, v67 row_mirror row_mask:0xf bank_mask:0xf
	s_and_saveexec_b64 s[4:5], s[36:37]
	s_cbranch_execz .LBB0_425
	s_waitcnt lgkmcnt(0)
	v_add_f32_e32 v71, v67, v71
	v_mov_b32_e32 v67, v1
	v_lshl_add_u64 v[134:135], v[104:105], 0, v[66:67]
	global_atomic_add_f32 v[134:135], v71, off offset:160
.LBB0_425:
	s_or_b64 exec, exec, s[4:5]
	ds_read_b128 v[140:143], v69 offset:11968
	v_lshlrev_b32_e32 v134, 16, v112
	v_and_b32_e32 v135, 0xffff0000, v112
	v_lshlrev_b32_e32 v112, 16, v113
	v_and_b32_e32 v113, 0xffff0000, v113
	s_waitcnt lgkmcnt(0)
	v_pk_add_f32 v[134:135], v[140:141], v[134:135]
	v_pk_add_f32 v[140:141], v[142:143], v[112:113]
	v_pk_mul_f32 v[112:113], v[134:135], v[134:135]
	v_pk_mul_f32 v[142:143], v[140:141], v[140:141]
	v_add_f32_e32 v67, v112, v113
	v_add_f32_e32 v67, v142, v67
	v_add_f32_e32 v67, v143, v67
	s_nop 1
	v_mov_b32_dpp v71, v67 quad_perm:[1,0,3,2] row_mask:0xf bank_mask:0xf
	v_or_b32_e32 v112, 44, v183
	v_cvt_pk_bf16_f32 v134, v134, v135
	v_cvt_pk_bf16_f32 v135, v140, v141
	v_lshlrev_b32_e32 v140, 11, v112
	s_waitcnt lgkmcnt(0)
	v_add_f32_e32 v67, v67, v71
	s_nop 1
	v_mov_b32_dpp v71, v67 quad_perm:[2,3,0,1] row_mask:0xf bank_mask:0xf
	v_mov_b32_e32 v141, v1
	v_lshl_add_u64 v[140:141], v[110:111], 0, v[140:141]
	global_store_dwordx2 v[140:141], v[134:135], off
	s_waitcnt lgkmcnt(0)
	v_add_f32_e32 v67, v67, v71
	s_nop 1
	v_mov_b32_dpp v71, v67 row_half_mirror row_mask:0xf bank_mask:0xf
	s_waitcnt lgkmcnt(0)
	v_add_f32_e32 v67, v67, v71
	s_nop 1
	v_mov_b32_dpp v71, v67 row_mirror row_mask:0xf bank_mask:0xf
	s_and_saveexec_b64 s[4:5], s[36:37]
	s_cbranch_execz .LBB0_427
	s_waitcnt lgkmcnt(0)
	v_add_f32_e32 v71, v67, v71
	v_mov_b32_e32 v67, v1
	v_lshl_add_u64 v[134:135], v[104:105], 0, v[66:67]
	global_atomic_add_f32 v[134:135], v71, off offset:176
; DI float bflo(unsigned v) { return __uint_as_float(v << 16); }
; DI float bfhi(unsigned v) { return __uint_as_float(v & 0xffff0000u); }
; template <int EPI>
; DI void gemm_tile(const Params& p, int layer, int mt, int nt, u16* sm, int wv) {
;     ...
;       for (int t = 0; t < 16; ++t) {
;         const int row = (lane >> 4) + 4 * t;
;         const f32x4 a4 = *(const f32x4*)(stg + row * 68 + kc * 4);
;         const float v0 = bflo(xb[t][0]) + a4[0], v1 = bfhi(xb[t][0]) + a4[1], v2 = bflo(xb[t][1]) + a4[2], v3 = bfhi(xb[t][1]) + a4[3];
;         float sq = v0 * v0 + v1 * v1 + v2 * v2 + v3 * v3;
;         u32x2 pv = {pk2(v0, v1), pk2(v2, v3)};
;         if (has_next) *(u32x2*)(xrow + (size_t)row * DM) = pv;
;         else *(u32x2*)(x2row + (size_t)row * DM) = pv;
;         sq += shx(sq, lane, 1); sq += shx(sq, lane, 2); sq += shx(sq, lane, 4); sq += shx(sq, lane, 8);
;         if (kc == 0) atomicAdd(ssn + mrow0 + row, sq);
.LBB0_427:
	s_or_b64 exec, exec, s[4:5]
	ds_read_b128 v[140:143], v69 offset:13056
	v_lshlrev_b32_e32 v134, 16, v108
	v_and_b32_e32 v135, 0xffff0000, v108
	v_lshlrev_b32_e32 v108, 16, v109
	v_and_b32_e32 v109, 0xffff0000, v109
	s_waitcnt lgkmcnt(0)
	v_pk_add_f32 v[134:135], v[140:141], v[134:135]
	v_pk_add_f32 v[140:141], v[142:143], v[108:109]
	v_pk_mul_f32 v[108:109], v[134:135], v[134:135]
	v_pk_mul_f32 v[142:143], v[140:141], v[140:141]
	v_add_f32_e32 v67, v108, v109
	v_add_f32_e32 v67, v142, v67
	v_add_f32_e32 v67, v143, v67
	s_nop 1
	v_mov_b32_dpp v71, v67 quad_perm:[1,0,3,2] row_mask:0xf bank_mask:0xf
	v_or_b32_e32 v108, 48, v183
	v_cvt_pk_bf16_f32 v134, v134, v135
	v_cvt_pk_bf16_f32 v135, v140, v141
	v_lshlrev_b32_e32 v140, 11, v108
	s_waitcnt lgkmcnt(0)
	v_add_f32_e32 v67, v67, v71
	s_nop 1
	v_mov_b32_dpp v71, v67 quad_perm:[2,3,0,1] row_mask:0xf bank_mask:0xf
	v_mov_b32_e32 v141, v1
	v_lshl_add_u64 v[140:141], v[110:111], 0, v[140:141]
	global_store_dwordx2 v[140:141], v[134:135], off
	s_waitcnt lgkmcnt(0)
	v_add_f32_e32 v67, v67, v71
	s_nop 1
	v_mov_b32_dpp v71, v67 row_half_mirror row_mask:0xf bank_mask:0xf
	s_waitcnt lgkmcnt(0)
	v_add_f32_e32 v67, v67, v71
	s_nop 1
	v_mov_b32_dpp v71, v67 row_mirror row_mask:0xf bank_mask:0xf
	s_and_saveexec_b64 s[4:5], s[36:37]
	s_cbranch_execz .LBB0_429
	s_waitcnt lgkmcnt(0)
	v_add_f32_e32 v71, v67, v71
	v_mov_b32_e32 v67, v1
	v_lshl_add_u64 v[134:135], v[104:105], 0, v[66:67]
	global_atomic_add_f32 v[134:135], v71, off offset:192
.LBB0_429:
	s_or_b64 exec, exec, s[4:5]
	ds_read_b128 v[140:143], v69 offset:14144
	s_waitcnt vmcnt(14)
	v_lshlrev_b32_e32 v134, 16, v106
	v_and_b32_e32 v135, 0xffff0000, v106
	v_lshlrev_b32_e32 v106, 16, v107
	v_and_b32_e32 v107, 0xffff0000, v107
	s_waitcnt lgkmcnt(0)
	v_pk_add_f32 v[134:135], v[140:141], v[134:135]
	v_pk_add_f32 v[140:141], v[142:143], v[106:107]
	v_pk_mul_f32 v[106:107], v[134:135], v[134:135]
	v_pk_mul_f32 v[142:143], v[140:141], v[140:141]
	v_add_f32_e32 v67, v106, v107
	v_add_f32_e32 v67, v142, v67
	v_add_f32_e32 v67, v143, v67
	s_nop 1
	v_mov_b32_dpp v71, v67 quad_perm:[1,0,3,2] row_mask:0xf bank_mask:0xf
	v_or_b32_e32 v106, 52, v183
	v_cvt_pk_bf16_f32 v134, v134, v135
	v_cvt_pk_bf16_f32 v135, v140, v141
	v_lshlrev_b32_e32 v140, 11, v106
	s_waitcnt lgkmcnt(0)
	v_add_f32_e32 v67, v67, v71
	s_nop 1
	v_mov_b32_dpp v71, v67 quad_perm:[2,3,0,1] row_mask:0xf bank_mask:0xf
	v_mov_b32_e32 v141, v1
	v_lshl_add_u64 v[140:141], v[110:111], 0, v[140:141]
	global_store_dwordx2 v[140:141], v[134:135], off
	s_waitcnt lgkmcnt(0)
	v_add_f32_e32 v67, v67, v71
	s_nop 1
	v_mov_b32_dpp v71, v67 row_half_mirror row_mask:0xf bank_mask:0xf
	s_waitcnt lgkmcnt(0)
	v_add_f32_e32 v67, v67, v71
	s_nop 1
	v_mov_b32_dpp v71, v67 row_mirror row_mask:0xf bank_mask:0xf
	s_and_saveexec_b64 s[4:5], s[36:37]
	s_cbranch_execz .LBB0_431
	s_waitcnt lgkmcnt(0)
	v_add_f32_e32 v71, v67, v71
	v_mov_b32_e32 v67, v1
	v_lshl_add_u64 v[134:135], v[104:105], 0, v[66:67]
	global_atomic_add_f32 v[134:135], v71, off offset:208
.LBB0_431:
	s_or_b64 exec, exec, s[4:5]
	ds_read_b128 v[140:143], v69 offset:15232
	s_waitcnt vmcnt(14)
	v_lshlrev_b32_e32 v134, 16, v102
	v_and_b32_e32 v135, 0xffff0000, v102
	v_lshlrev_b32_e32 v102, 16, v103
	v_and_b32_e32 v103, 0xffff0000, v103
	s_waitcnt lgkmcnt(0)
	v_pk_add_f32 v[134:135], v[140:141], v[134:135]
	v_pk_add_f32 v[140:141], v[142:143], v[102:103]
	v_pk_mul_f32 v[102:103], v[134:135], v[134:135]
	v_pk_mul_f32 v[142:143], v[140:141], v[140:141]
	v_add_f32_e32 v67, v102, v103
	v_add_f32_e32 v67, v142, v67
	v_add_f32_e32 v67, v143, v67
	s_nop 1
	v_mov_b32_dpp v71, v67 quad_perm:[1,0,3,2] row_mask:0xf bank_mask:0xf
	v_or_b32_e32 v103, 56, v183
	v_cvt_pk_bf16_f32 v134, v134, v135
	v_cvt_pk_bf16_f32 v135, v140, v141
	v_lshlrev_b32_e32 v140, 11, v103
	s_waitcnt lgkmcnt(0)
	v_add_f32_e32 v67, v67, v71
	s_nop 1
	v_mov_b32_dpp v71, v67 quad_perm:[2,3,0,1] row_mask:0xf bank_mask:0xf
	v_mov_b32_e32 v141, v1
	v_lshl_add_u64 v[140:141], v[110:111], 0, v[140:141]
	global_store_dwordx2 v[140:141], v[134:135], off
	s_waitcnt lgkmcnt(0)
	v_add_f32_e32 v67, v67, v71
	s_nop 1
	v_mov_b32_dpp v71, v67 row_half_mirror row_mask:0xf bank_mask:0xf
	s_waitcnt lgkmcnt(0)
	v_add_f32_e32 v67, v67, v71
	s_nop 1
	v_mov_b32_dpp v71, v67 row_mirror row_mask:0xf bank_mask:0xf
	s_and_saveexec_b64 s[4:5], s[36:37]
	s_cbranch_execz .LBB0_433
	s_waitcnt lgkmcnt(0)
	v_add_f32_e32 v71, v67, v71
	v_mov_b32_e32 v67, v1
	v_lshl_add_u64 v[134:135], v[104:105], 0, v[66:67]
	global_atomic_add_f32 v[134:135], v71, off offset:224
.LBB0_433:
	s_or_b64 exec, exec, s[4:5]
	ds_read_b128 v[140:143], v69 offset:16320
	s_waitcnt vmcnt(14)
	v_lshlrev_b32_e32 v134, 16, v100
	v_and_b32_e32 v135, 0xffff0000, v100
	v_lshlrev_b32_e32 v100, 16, v101
	v_and_b32_e32 v101, 0xffff0000, v101
	s_waitcnt lgkmcnt(0)
	v_pk_add_f32 v[134:135], v[140:141], v[134:135]
	v_pk_add_f32 v[100:101], v[142:143], v[100:101]
	v_pk_mul_f32 v[140:141], v[134:135], v[134:135]
	v_pk_mul_f32 v[142:143], v[100:101], v[100:101]
	v_add_f32_e32 v67, v140, v141
	v_add_f32_e32 v67, v142, v67
	v_add_f32_e32 v67, v143, v67
	s_nop 1
	v_mov_b32_dpp v71, v67 quad_perm:[1,0,3,2] row_mask:0xf bank_mask:0xf
	v_or_b32_e32 v102, 60, v183
	v_cvt_pk_bf16_f32 v134, v134, v135
	v_cvt_pk_bf16_f32 v135, v100, v101
	v_lshlrev_b32_e32 v100, 11, v102
	s_waitcnt lgkmcnt(0)
	v_add_f32_e32 v67, v67, v71
	s_nop 1
	v_mov_b32_dpp v71, v67 quad_perm:[2,3,0,1] row_mask:0xf bank_mask:0xf
	v_mov_b32_e32 v101, v1
	v_lshl_add_u64 v[100:101], v[110:111], 0, v[100:101]
	global_store_dwordx2 v[100:101], v[134:135], off
	s_waitcnt lgkmcnt(0)
	v_add_f32_e32 v67, v67, v71
	s_nop 1
	v_mov_b32_dpp v71, v67 row_half_mirror row_mask:0xf bank_mask:0xf
	s_waitcnt lgkmcnt(0)
	v_add_f32_e32 v67, v67, v71
	s_nop 1
	v_mov_b32_dpp v71, v67 row_mirror row_mask:0xf bank_mask:0xf
	s_and_saveexec_b64 s[4:5], s[36:37]
	s_cbranch_execz .LBB0_435
	s_waitcnt lgkmcnt(0)
	v_add_f32_e32 v71, v67, v71
	v_mov_b32_e32 v67, v1
	v_lshl_add_u64 v[100:101], v[104:105], 0, v[66:67]
	global_atomic_add_f32 v[100:101], v71, off offset:240

; DI float bflo(unsigned v) { return __uint_as_float(v << 16); }
; DI float bfhi(unsigned v) { return __uint_as_float(v & 0xffff0000u); }
; template <int EPI>
; DI void gemm_tile(const Params& p, int layer, int mt, int nt, u16* sm, int wv) {
;     ...
;       for (int t = 0; t < 16; ++t) {
;         const int row = (lane >> 4) + 4 * t;
;         const f32x4 a4 = *(const f32x4*)(stg + row * 68 + kc * 4);
;         const float v0 = bflo(xb[t][0]) + a4[0], v1 = bfhi(xb[t][0]) + a4[1], v2 = bflo(xb[t][1]) + a4[2], v3 = bfhi(xb[t][1]) + a4[3];
;         float sq = v0 * v0 + v1 * v1 + v2 * v2 + v3 * v3;
;         u32x2 pv = {pk2(v0, v1), pk2(v2, v3)};
;         if (has_next) *(u32x2*)(xrow + (size_t)row * DM) = pv;
;         else *(u32x2*)(x2row + (size_t)row * DM) = pv;
;         sq += shx(sq, lane, 1); sq += shx(sq, lane, 2); sq += shx(sq, lane, 4); sq += shx(sq, lane, 8);
;         if (kc == 0) atomicAdd(ssn + mrow0 + row, sq);
.LBB0_439:
	v_pk_mul_f32 v[36:37], v[40:41], v[40:41]
	v_pk_mul_f32 v[40:41], v[42:43], v[42:43]
	v_add_f32_e32 v0, v36, v37
	v_add_f32_e32 v0, v40, v0
	v_add_f32_e32 v0, v41, v0
	s_nop 1
	v_mov_b32_dpp v36, v0 quad_perm:[1,0,3,2] row_mask:0xf bank_mask:0xf
	s_waitcnt lgkmcnt(0)
	v_add_f32_e32 v0, v0, v36
	s_nop 1
	v_mov_b32_dpp v36, v0 quad_perm:[2,3,0,1] row_mask:0xf bank_mask:0xf
	s_waitcnt lgkmcnt(0)
	v_add_f32_e32 v0, v0, v36
	s_nop 1
	v_mov_b32_dpp v36, v0 row_half_mirror row_mask:0xf bank_mask:0xf
	s_waitcnt lgkmcnt(0)
	v_add_f32_e32 v0, v0, v36
	s_nop 1
	v_mov_b32_dpp v36, v0 row_mirror row_mask:0xf bank_mask:0xf
	s_and_saveexec_b64 s[2:3], s[36:37]
	s_cbranch_execz .LBB0_441
	v_mov_b32_e32 v67, v1
	s_waitcnt lgkmcnt(0)
	v_add_f32_e32 v0, v0, v36
	v_lshl_add_u64 v[36:37], s[0:1], 0, v[66:67]
	v_lshl_add_u64 v[36:37], v[4:5], 2, v[36:37]
	global_atomic_add_f32 v[36:37], v0, off
.LBB0_441:
	s_or_b64 exec, exec, s[2:3]
	ds_read_b128 v[40:43], v69 offset:1088
	s_waitcnt lgkmcnt(1)
	v_lshlrev_b32_e32 v36, 16, v34
	v_and_b32_e32 v37, 0xffff0000, v34
	v_lshlrev_b32_e32 v34, 16, v35
	v_and_b32_e32 v35, 0xffff0000, v35
	s_waitcnt lgkmcnt(0)
	v_pk_add_f32 v[36:37], v[40:41], v[36:37]
	v_pk_add_f32 v[34:35], v[42:43], v[34:35]
	v_pk_mul_f32 v[40:41], v[36:37], v[36:37]
	v_pk_mul_f32 v[42:43], v[34:35], v[34:35]
	v_add_f32_e32 v40, v40, v41
	v_lshlrev_b32_e32 v0, 10, v132
	v_add_f32_e32 v40, v42, v40
	v_add_f32_e32 v40, v43, v40
	v_cndmask_b32_e64 v11, v39, v11, s[34:35]
	v_cndmask_b32_e64 v10, v38, v10, s[34:35]
	v_lshlrev_b32_e32 v0, 1, v0
	v_cvt_pk_bf16_f32 v36, v36, v37
	v_cvt_pk_bf16_f32 v37, v34, v35
	v_lshl_add_u64 v[34:35], v[10:11], 0, v[0:1]
	s_nop 1
	v_mov_b32_dpp v0, v40 quad_perm:[1,0,3,2] row_mask:0xf bank_mask:0xf
	global_store_dwordx2 v[34:35], v[36:37], off
	v_lshl_add_u64 v[4:5], v[4:5], 2, s[0:1]
	s_waitcnt lgkmcnt(0)
	v_add_f32_e32 v0, v40, v0
	s_nop 1
	v_mov_b32_dpp v34, v0 quad_perm:[2,3,0,1] row_mask:0xf bank_mask:0xf
	s_waitcnt lgkmcnt(0)
	v_add_f32_e32 v0, v0, v34
	s_nop 1
	v_mov_b32_dpp v34, v0 row_half_mirror row_mask:0xf bank_mask:0xf
	s_waitcnt lgkmcnt(0)
	v_add_f32_e32 v0, v0, v34
	s_nop 1
	v_mov_b32_dpp v34, v0 row_mirror row_mask:0xf bank_mask:0xf
	s_and_saveexec_b64 s[2:3], s[36:37]
	s_cbranch_execz .LBB0_443
	v_mov_b32_e32 v67, v1
	s_waitcnt lgkmcnt(0)
	v_add_f32_e32 v0, v0, v34
	v_lshl_add_u64 v[34:35], v[4:5], 0, v[66:67]
	global_atomic_add_f32 v[34:35], v0, off offset:16
.LBB0_443:
	s_or_b64 exec, exec, s[2:3]
	s_waitcnt lgkmcnt(0)
	ds_read_b128 v[34:37], v69 offset:2176
	v_lshlrev_b32_e32 v38, 16, v32
	v_and_b32_e32 v39, 0xffff0000, v32
	v_lshlrev_b32_e32 v32, 16, v33
	v_and_b32_e32 v33, 0xffff0000, v33
	s_waitcnt lgkmcnt(0)
	v_pk_add_f32 v[34:35], v[34:35], v[38:39]
	v_pk_add_f32 v[32:33], v[36:37], v[32:33]
	v_pk_mul_f32 v[36:37], v[34:35], v[34:35]
	v_pk_mul_f32 v[38:39], v[32:33], v[32:33]
	v_add_f32_e32 v36, v36, v37
	v_lshlrev_b32_e32 v0, 10, v130
	v_add_f32_e32 v36, v38, v36
	v_add_f32_e32 v36, v39, v36
	v_lshlrev_b32_e32 v0, 1, v0
	v_cvt_pk_bf16_f32 v34, v34, v35
	v_cvt_pk_bf16_f32 v35, v32, v33
	v_lshl_add_u64 v[32:33], v[10:11], 0, v[0:1]
	s_nop 1
	v_mov_b32_dpp v0, v36 quad_perm:[1,0,3,2] row_mask:0xf bank_mask:0xf
	global_store_dwordx2 v[32:33], v[34:35], off
	s_waitcnt lgkmcnt(0)
	v_add_f32_e32 v0, v36, v0
	s_nop 1
	v_mov_b32_dpp v32, v0 quad_perm:[2,3,0,1] row_mask:0xf bank_mask:0xf
	s_waitcnt lgkmcnt(0)
	v_add_f32_e32 v0, v0, v32
	s_nop 1
	v_mov_b32_dpp v32, v0 row_half_mirror row_mask:0xf bank_mask:0xf
	s_waitcnt lgkmcnt(0)
	v_add_f32_e32 v0, v0, v32
	s_nop 1
	v_mov_b32_dpp v32, v0 row_mirror row_mask:0xf bank_mask:0xf
	s_and_saveexec_b64 s[2:3], s[36:37]
	s_cbranch_execz .LBB0_445
	v_mov_b32_e32 v67, v1
	s_waitcnt lgkmcnt(0)
	v_add_f32_e32 v0, v0, v32
	v_lshl_add_u64 v[32:33], v[4:5], 0, v[66:67]
	global_atomic_add_f32 v[32:33], v0, off offset:32
.LBB0_445:
	s_or_b64 exec, exec, s[2:3]
	s_waitcnt lgkmcnt(0)
	ds_read_b128 v[32:35], v69 offset:3264
	v_lshlrev_b32_e32 v36, 16, v30
	v_and_b32_e32 v37, 0xffff0000, v30
	v_lshlrev_b32_e32 v30, 16, v31
	v_and_b32_e32 v31, 0xffff0000, v31
	s_waitcnt lgkmcnt(0)
	v_pk_add_f32 v[32:33], v[32:33], v[36:37]
	v_pk_add_f32 v[30:31], v[34:35], v[30:31]
	v_pk_mul_f32 v[34:35], v[32:33], v[32:33]
	v_pk_mul_f32 v[36:37], v[30:31], v[30:31]
	v_add_f32_e32 v34, v34, v35
	v_lshlrev_b32_e32 v0, 10, v128
	v_add_f32_e32 v34, v36, v34
	v_add_f32_e32 v34, v37, v34
	v_lshlrev_b32_e32 v0, 1, v0
	v_cvt_pk_bf16_f32 v32, v32, v33
	v_cvt_pk_bf16_f32 v33, v30, v31
	v_lshl_add_u64 v[30:31], v[10:11], 0, v[0:1]
	s_nop 1
	v_mov_b32_dpp v0, v34 quad_perm:[1,0,3,2] row_mask:0xf bank_mask:0xf
	global_store_dwordx2 v[30:31], v[32:33], off
	s_waitcnt lgkmcnt(0)
	v_add_f32_e32 v0, v34, v0
	s_nop 1
	v_mov_b32_dpp v30, v0 quad_perm:[2,3,0,1] row_mask:0xf bank_mask:0xf
	s_waitcnt lgkmcnt(0)
	v_add_f32_e32 v0, v0, v30
	s_nop 1
	v_mov_b32_dpp v30, v0 row_half_mirror row_mask:0xf bank_mask:0xf
	s_waitcnt lgkmcnt(0)
	v_add_f32_e32 v0, v0, v30
	s_nop 1
	v_mov_b32_dpp v30, v0 row_mirror row_mask:0xf bank_mask:0xf
	s_and_saveexec_b64 s[2:3], s[36:37]
	s_cbranch_execz .LBB0_447
	v_mov_b32_e32 v67, v1
	s_waitcnt lgkmcnt(0)
	v_add_f32_e32 v0, v0, v30
	v_lshl_add_u64 v[30:31], v[4:5], 0, v[66:67]
	global_atomic_add_f32 v[30:31], v0, off offset:48
; DI float bflo(unsigned v) { return __uint_as_float(v << 16); }
; DI float bfhi(unsigned v) { return __uint_as_float(v & 0xffff0000u); }
; template <int EPI>
; DI void gemm_tile(const Params& p, int layer, int mt, int nt, u16* sm, int wv) {
;     ...
;       for (int t = 0; t < 16; ++t) {
;         const int row = (lane >> 4) + 4 * t;
;         const f32x4 a4 = *(const f32x4*)(stg + row * 68 + kc * 4);
;         const float v0 = bflo(xb[t][0]) + a4[0], v1 = bfhi(xb[t][0]) + a4[1], v2 = bflo(xb[t][1]) + a4[2], v3 = bfhi(xb[t][1]) + a4[3];
;         float sq = v0 * v0 + v1 * v1 + v2 * v2 + v3 * v3;
;         u32x2 pv = {pk2(v0, v1), pk2(v2, v3)};
;         if (has_next) *(u32x2*)(xrow + (size_t)row * DM) = pv;
;         else *(u32x2*)(x2row + (size_t)row * DM) = pv;
;         sq += shx(sq, lane, 1); sq += shx(sq, lane, 2); sq += shx(sq, lane, 4); sq += shx(sq, lane, 8);
;         if (kc == 0) atomicAdd(ssn + mrow0 + row, sq);
.LBB0_447:
	s_or_b64 exec, exec, s[2:3]
	s_waitcnt lgkmcnt(0)
	ds_read_b128 v[30:33], v69 offset:4352
	v_lshlrev_b32_e32 v34, 16, v28
	v_and_b32_e32 v35, 0xffff0000, v28
	v_lshlrev_b32_e32 v28, 16, v29
	v_and_b32_e32 v29, 0xffff0000, v29
	s_waitcnt lgkmcnt(0)
	v_pk_add_f32 v[30:31], v[30:31], v[34:35]
	v_pk_add_f32 v[28:29], v[32:33], v[28:29]
	v_pk_mul_f32 v[32:33], v[30:31], v[30:31]
	v_pk_mul_f32 v[34:35], v[28:29], v[28:29]
	v_add_f32_e32 v32, v32, v33
	v_lshlrev_b32_e32 v0, 10, v126
	v_add_f32_e32 v32, v34, v32
	v_add_f32_e32 v32, v35, v32
	v_lshlrev_b32_e32 v0, 1, v0
	v_cvt_pk_bf16_f32 v30, v30, v31
	v_cvt_pk_bf16_f32 v31, v28, v29
	v_lshl_add_u64 v[28:29], v[10:11], 0, v[0:1]
	s_nop 1
	v_mov_b32_dpp v0, v32 quad_perm:[1,0,3,2] row_mask:0xf bank_mask:0xf
	global_store_dwordx2 v[28:29], v[30:31], off
	s_waitcnt lgkmcnt(0)
	v_add_f32_e32 v0, v32, v0
	s_nop 1
	v_mov_b32_dpp v28, v0 quad_perm:[2,3,0,1] row_mask:0xf bank_mask:0xf
	s_waitcnt lgkmcnt(0)
	v_add_f32_e32 v0, v0, v28
	s_nop 1
	v_mov_b32_dpp v28, v0 row_half_mirror row_mask:0xf bank_mask:0xf
	s_waitcnt lgkmcnt(0)
	v_add_f32_e32 v0, v0, v28
	s_nop 1
	v_mov_b32_dpp v28, v0 row_mirror row_mask:0xf bank_mask:0xf
	s_and_saveexec_b64 s[2:3], s[36:37]
	s_cbranch_execz .LBB0_449
	v_mov_b32_e32 v67, v1
	s_waitcnt lgkmcnt(0)
	v_add_f32_e32 v0, v0, v28
	v_lshl_add_u64 v[28:29], v[4:5], 0, v[66:67]
	global_atomic_add_f32 v[28:29], v0, off offset:64
.LBB0_449:
	s_or_b64 exec, exec, s[2:3]
	s_waitcnt lgkmcnt(0)
	ds_read_b128 v[28:31], v69 offset:5440
	v_lshlrev_b32_e32 v32, 16, v26
	v_and_b32_e32 v33, 0xffff0000, v26
	v_lshlrev_b32_e32 v26, 16, v27
	v_and_b32_e32 v27, 0xffff0000, v27
	s_waitcnt lgkmcnt(0)
	v_pk_add_f32 v[28:29], v[28:29], v[32:33]
	v_pk_add_f32 v[26:27], v[30:31], v[26:27]
	v_pk_mul_f32 v[30:31], v[28:29], v[28:29]
	v_pk_mul_f32 v[32:33], v[26:27], v[26:27]
	v_add_f32_e32 v30, v30, v31
	v_lshlrev_b32_e32 v0, 10, v124
	v_add_f32_e32 v30, v32, v30
	v_add_f32_e32 v30, v33, v30
	v_lshlrev_b32_e32 v0, 1, v0
	v_cvt_pk_bf16_f32 v28, v28, v29
	v_cvt_pk_bf16_f32 v29, v26, v27
	v_lshl_add_u64 v[26:27], v[10:11], 0, v[0:1]
	s_nop 1
	v_mov_b32_dpp v0, v30 quad_perm:[1,0,3,2] row_mask:0xf bank_mask:0xf
	global_store_dwordx2 v[26:27], v[28:29], off
	s_waitcnt lgkmcnt(0)
	v_add_f32_e32 v0, v30, v0
	s_nop 1
	v_mov_b32_dpp v26, v0 quad_perm:[2,3,0,1] row_mask:0xf bank_mask:0xf
	s_waitcnt lgkmcnt(0)
	v_add_f32_e32 v0, v0, v26
	s_nop 1
	v_mov_b32_dpp v26, v0 row_half_mirror row_mask:0xf bank_mask:0xf
	s_waitcnt lgkmcnt(0)
	v_add_f32_e32 v0, v0, v26
	s_nop 1
	v_mov_b32_dpp v26, v0 row_mirror row_mask:0xf bank_mask:0xf
	s_and_saveexec_b64 s[2:3], s[36:37]
	s_cbranch_execz .LBB0_451
	v_mov_b32_e32 v67, v1
	s_waitcnt lgkmcnt(0)
	v_add_f32_e32 v0, v0, v26
	v_lshl_add_u64 v[26:27], v[4:5], 0, v[66:67]
	global_atomic_add_f32 v[26:27], v0, off offset:80
.LBB0_451:
	s_or_b64 exec, exec, s[2:3]
	s_waitcnt lgkmcnt(0)
	ds_read_b128 v[26:29], v69 offset:6528
	v_lshlrev_b32_e32 v30, 16, v24
	v_and_b32_e32 v31, 0xffff0000, v24
	v_lshlrev_b32_e32 v24, 16, v25
	v_and_b32_e32 v25, 0xffff0000, v25
	s_waitcnt lgkmcnt(0)
	v_pk_add_f32 v[26:27], v[26:27], v[30:31]
	v_pk_add_f32 v[24:25], v[28:29], v[24:25]
	v_pk_mul_f32 v[28:29], v[26:27], v[26:27]
	v_pk_mul_f32 v[30:31], v[24:25], v[24:25]
	v_add_f32_e32 v28, v28, v29
	v_lshlrev_b32_e32 v0, 10, v122
	v_add_f32_e32 v28, v30, v28
	v_add_f32_e32 v28, v31, v28
	v_lshlrev_b32_e32 v0, 1, v0
	v_cvt_pk_bf16_f32 v26, v26, v27
	v_cvt_pk_bf16_f32 v27, v24, v25
	v_lshl_add_u64 v[24:25], v[10:11], 0, v[0:1]
	s_nop 1
	v_mov_b32_dpp v0, v28 quad_perm:[1,0,3,2] row_mask:0xf bank_mask:0xf
	global_store_dwordx2 v[24:25], v[26:27], off
	s_waitcnt lgkmcnt(0)
	v_add_f32_e32 v0, v28, v0
	s_nop 1
	v_mov_b32_dpp v24, v0 quad_perm:[2,3,0,1] row_mask:0xf bank_mask:0xf
	s_waitcnt lgkmcnt(0)
	v_add_f32_e32 v0, v0, v24
	s_nop 1
	v_mov_b32_dpp v24, v0 row_half_mirror row_mask:0xf bank_mask:0xf
	s_waitcnt lgkmcnt(0)
	v_add_f32_e32 v0, v0, v24
	s_nop 1
	v_mov_b32_dpp v24, v0 row_mirror row_mask:0xf bank_mask:0xf
	s_and_saveexec_b64 s[2:3], s[36:37]
	s_cbranch_execz .LBB0_453
	v_mov_b32_e32 v67, v1
	s_waitcnt lgkmcnt(0)
	v_add_f32_e32 v0, v0, v24
	v_lshl_add_u64 v[24:25], v[4:5], 0, v[66:67]
	global_atomic_add_f32 v[24:25], v0, off offset:96
.LBB0_453:
	s_or_b64 exec, exec, s[2:3]
	s_waitcnt lgkmcnt(0)
	ds_read_b128 v[24:27], v69 offset:7616
	v_lshlrev_b32_e32 v28, 16, v22
	v_and_b32_e32 v29, 0xffff0000, v22
	v_lshlrev_b32_e32 v22, 16, v23
	v_and_b32_e32 v23, 0xffff0000, v23
	s_waitcnt lgkmcnt(0)
	v_pk_add_f32 v[24:25], v[24:25], v[28:29]
	v_pk_add_f32 v[22:23], v[26:27], v[22:23]
	v_pk_mul_f32 v[26:27], v[24:25], v[24:25]
	v_pk_mul_f32 v[28:29], v[22:23], v[22:23]
	v_add_f32_e32 v26, v26, v27
	v_lshlrev_b32_e32 v0, 10, v120
	v_add_f32_e32 v26, v28, v26
	v_add_f32_e32 v26, v29, v26
	v_lshlrev_b32_e32 v0, 1, v0
	v_cvt_pk_bf16_f32 v24, v24, v25
	v_cvt_pk_bf16_f32 v25, v22, v23
	v_lshl_add_u64 v[22:23], v[10:11], 0, v[0:1]
	s_nop 1
	v_mov_b32_dpp v0, v26 quad_perm:[1,0,3,2] row_mask:0xf bank_mask:0xf
	global_store_dwordx2 v[22:23], v[24:25], off
	s_waitcnt lgkmcnt(0)
	v_add_f32_e32 v0, v26, v0
	s_nop 1
	v_mov_b32_dpp v22, v0 quad_perm:[2,3,0,1] row_mask:0xf bank_mask:0xf
	s_waitcnt lgkmcnt(0)
	v_add_f32_e32 v0, v0, v22
	s_nop 1
	v_mov_b32_dpp v22, v0 row_half_mirror row_mask:0xf bank_mask:0xf
	s_waitcnt lgkmcnt(0)
	v_add_f32_e32 v0, v0, v22
	s_nop 1
	v_mov_b32_dpp v22, v0 row_mirror row_mask:0xf bank_mask:0xf
	s_and_saveexec_b64 s[2:3], s[36:37]
	s_cbranch_execz .LBB0_455
	v_mov_b32_e32 v67, v1
	s_waitcnt lgkmcnt(0)
	v_add_f32_e32 v0, v0, v22
	v_lshl_add_u64 v[22:23], v[4:5], 0, v[66:67]
	global_atomic_add_f32 v[22:23], v0, off offset:112
; DI float bflo(unsigned v) { return __uint_as_float(v << 16); }
; DI float bfhi(unsigned v) { return __uint_as_float(v & 0xffff0000u); }
; template <int EPI>
; DI void gemm_tile(const Params& p, int layer, int mt, int nt, u16* sm, int wv) {
;     ...
;       for (int t = 0; t < 16; ++t) {
;         const int row = (lane >> 4) + 4 * t;
;         const f32x4 a4 = *(const f32x4*)(stg + row * 68 + kc * 4);
;         const float v0 = bflo(xb[t][0]) + a4[0], v1 = bfhi(xb[t][0]) + a4[1], v2 = bflo(xb[t][1]) + a4[2], v3 = bfhi(xb[t][1]) + a4[3];
;         float sq = v0 * v0 + v1 * v1 + v2 * v2 + v3 * v3;
;         u32x2 pv = {pk2(v0, v1), pk2(v2, v3)};
;         if (has_next) *(u32x2*)(xrow + (size_t)row * DM) = pv;
;         else *(u32x2*)(x2row + (size_t)row * DM) = pv;
;         sq += shx(sq, lane, 1); sq += shx(sq, lane, 2); sq += shx(sq, lane, 4); sq += shx(sq, lane, 8);
;         if (kc == 0) atomicAdd(ssn + mrow0 + row, sq);
.LBB0_455:
	s_or_b64 exec, exec, s[2:3]
	s_waitcnt lgkmcnt(0)
	ds_read_b128 v[22:25], v69 offset:8704
	v_lshlrev_b32_e32 v26, 16, v20
	v_and_b32_e32 v27, 0xffff0000, v20
	v_lshlrev_b32_e32 v20, 16, v21
	v_and_b32_e32 v21, 0xffff0000, v21
	s_waitcnt lgkmcnt(0)
	v_pk_add_f32 v[22:23], v[22:23], v[26:27]
	v_pk_add_f32 v[20:21], v[24:25], v[20:21]
	v_pk_mul_f32 v[24:25], v[22:23], v[22:23]
	v_pk_mul_f32 v[26:27], v[20:21], v[20:21]
	v_add_f32_e32 v24, v24, v25
	v_lshlrev_b32_e32 v0, 10, v118
	v_add_f32_e32 v24, v26, v24
	v_add_f32_e32 v24, v27, v24
	v_lshlrev_b32_e32 v0, 1, v0
	v_cvt_pk_bf16_f32 v22, v22, v23
	v_cvt_pk_bf16_f32 v23, v20, v21
	v_lshl_add_u64 v[20:21], v[10:11], 0, v[0:1]
	s_nop 1
	v_mov_b32_dpp v0, v24 quad_perm:[1,0,3,2] row_mask:0xf bank_mask:0xf
	global_store_dwordx2 v[20:21], v[22:23], off
	s_waitcnt lgkmcnt(0)
	v_add_f32_e32 v0, v24, v0
	s_nop 1
	v_mov_b32_dpp v20, v0 quad_perm:[2,3,0,1] row_mask:0xf bank_mask:0xf
	s_waitcnt lgkmcnt(0)
	v_add_f32_e32 v0, v0, v20
	s_nop 1
	v_mov_b32_dpp v20, v0 row_half_mirror row_mask:0xf bank_mask:0xf
	s_waitcnt lgkmcnt(0)
	v_add_f32_e32 v0, v0, v20
	s_nop 1
	v_mov_b32_dpp v20, v0 row_mirror row_mask:0xf bank_mask:0xf
	s_and_saveexec_b64 s[2:3], s[36:37]
	s_cbranch_execz .LBB0_457
	v_mov_b32_e32 v67, v1
	s_waitcnt lgkmcnt(0)
	v_add_f32_e32 v0, v0, v20
	v_lshl_add_u64 v[20:21], v[4:5], 0, v[66:67]
	global_atomic_add_f32 v[20:21], v0, off offset:128
.LBB0_457:
	s_or_b64 exec, exec, s[2:3]
	s_waitcnt lgkmcnt(0)
	ds_read_b128 v[20:23], v69 offset:9792
	v_lshlrev_b32_e32 v24, 16, v18
	v_and_b32_e32 v25, 0xffff0000, v18
	v_lshlrev_b32_e32 v18, 16, v19
	v_and_b32_e32 v19, 0xffff0000, v19
	s_waitcnt lgkmcnt(0)
	v_pk_add_f32 v[20:21], v[20:21], v[24:25]
	v_pk_add_f32 v[18:19], v[22:23], v[18:19]
	v_pk_mul_f32 v[22:23], v[20:21], v[20:21]
	v_pk_mul_f32 v[24:25], v[18:19], v[18:19]
	v_add_f32_e32 v22, v22, v23
	v_lshlrev_b32_e32 v0, 10, v116
	v_add_f32_e32 v22, v24, v22
	v_add_f32_e32 v22, v25, v22
	v_lshlrev_b32_e32 v0, 1, v0
	v_cvt_pk_bf16_f32 v20, v20, v21
	v_cvt_pk_bf16_f32 v21, v18, v19
	v_lshl_add_u64 v[18:19], v[10:11], 0, v[0:1]
	s_nop 1
	v_mov_b32_dpp v0, v22 quad_perm:[1,0,3,2] row_mask:0xf bank_mask:0xf
	global_store_dwordx2 v[18:19], v[20:21], off
	s_waitcnt lgkmcnt(0)
	v_add_f32_e32 v0, v22, v0
	s_nop 1
	v_mov_b32_dpp v18, v0 quad_perm:[2,3,0,1] row_mask:0xf bank_mask:0xf
	s_waitcnt lgkmcnt(0)
	v_add_f32_e32 v0, v0, v18
	s_nop 1
	v_mov_b32_dpp v18, v0 row_half_mirror row_mask:0xf bank_mask:0xf
	s_waitcnt lgkmcnt(0)
	v_add_f32_e32 v0, v0, v18
	s_nop 1
	v_mov_b32_dpp v18, v0 row_mirror row_mask:0xf bank_mask:0xf
	s_and_saveexec_b64 s[2:3], s[36:37]
	s_cbranch_execz .LBB0_459
	v_mov_b32_e32 v67, v1
	s_waitcnt lgkmcnt(0)
	v_add_f32_e32 v0, v0, v18
	v_lshl_add_u64 v[18:19], v[4:5], 0, v[66:67]
	global_atomic_add_f32 v[18:19], v0, off offset:144
.LBB0_459:
	s_or_b64 exec, exec, s[2:3]
	s_waitcnt lgkmcnt(0)
	ds_read_b128 v[18:21], v69 offset:10880
	v_lshlrev_b32_e32 v22, 16, v16
	v_and_b32_e32 v23, 0xffff0000, v16
	v_lshlrev_b32_e32 v16, 16, v17
	v_and_b32_e32 v17, 0xffff0000, v17
	s_waitcnt lgkmcnt(0)
	v_pk_add_f32 v[18:19], v[18:19], v[22:23]
	v_pk_add_f32 v[16:17], v[20:21], v[16:17]
	v_pk_mul_f32 v[20:21], v[18:19], v[18:19]
	v_pk_mul_f32 v[22:23], v[16:17], v[16:17]
	v_add_f32_e32 v20, v20, v21
	v_lshlrev_b32_e32 v0, 10, v114
	v_add_f32_e32 v20, v22, v20
	v_add_f32_e32 v20, v23, v20
	v_lshlrev_b32_e32 v0, 1, v0
	v_cvt_pk_bf16_f32 v18, v18, v19
	v_cvt_pk_bf16_f32 v19, v16, v17
	v_lshl_add_u64 v[16:17], v[10:11], 0, v[0:1]
	s_nop 1
	v_mov_b32_dpp v0, v20 quad_perm:[1,0,3,2] row_mask:0xf bank_mask:0xf
	global_store_dwordx2 v[16:17], v[18:19], off
	s_waitcnt lgkmcnt(0)
	v_add_f32_e32 v0, v20, v0
	s_nop 1
	v_mov_b32_dpp v16, v0 quad_perm:[2,3,0,1] row_mask:0xf bank_mask:0xf
	s_waitcnt lgkmcnt(0)
	v_add_f32_e32 v0, v0, v16
	s_nop 1
	v_mov_b32_dpp v16, v0 row_half_mirror row_mask:0xf bank_mask:0xf
	s_waitcnt lgkmcnt(0)
	v_add_f32_e32 v0, v0, v16
	s_nop 1
	v_mov_b32_dpp v16, v0 row_mirror row_mask:0xf bank_mask:0xf
	s_and_saveexec_b64 s[2:3], s[36:37]
	s_cbranch_execz .LBB0_461
	v_mov_b32_e32 v67, v1
	s_waitcnt lgkmcnt(0)
	v_add_f32_e32 v0, v0, v16
	v_lshl_add_u64 v[16:17], v[4:5], 0, v[66:67]
	global_atomic_add_f32 v[16:17], v0, off offset:160
.LBB0_461:
	s_or_b64 exec, exec, s[2:3]
	s_waitcnt lgkmcnt(0)
	ds_read_b128 v[16:19], v69 offset:11968
	v_lshlrev_b32_e32 v20, 16, v14
	v_and_b32_e32 v21, 0xffff0000, v14
	v_lshlrev_b32_e32 v14, 16, v15
	v_and_b32_e32 v15, 0xffff0000, v15
	s_waitcnt lgkmcnt(0)
	v_pk_add_f32 v[16:17], v[16:17], v[20:21]
	v_pk_add_f32 v[14:15], v[18:19], v[14:15]
	v_pk_mul_f32 v[18:19], v[16:17], v[16:17]
	v_pk_mul_f32 v[20:21], v[14:15], v[14:15]
	v_add_f32_e32 v18, v18, v19
	v_lshlrev_b32_e32 v0, 10, v112
	v_add_f32_e32 v18, v20, v18
	v_add_f32_e32 v18, v21, v18
	v_lshlrev_b32_e32 v0, 1, v0
	v_cvt_pk_bf16_f32 v16, v16, v17
	v_cvt_pk_bf16_f32 v17, v14, v15
	v_lshl_add_u64 v[14:15], v[10:11], 0, v[0:1]
	s_nop 1
	v_mov_b32_dpp v0, v18 quad_perm:[1,0,3,2] row_mask:0xf bank_mask:0xf
	global_store_dwordx2 v[14:15], v[16:17], off
	s_waitcnt lgkmcnt(0)
	v_add_f32_e32 v0, v18, v0
	s_nop 1
	v_mov_b32_dpp v14, v0 quad_perm:[2,3,0,1] row_mask:0xf bank_mask:0xf
	s_waitcnt lgkmcnt(0)
	v_add_f32_e32 v0, v0, v14
	s_nop 1
	v_mov_b32_dpp v14, v0 row_half_mirror row_mask:0xf bank_mask:0xf
	s_waitcnt lgkmcnt(0)
	v_add_f32_e32 v0, v0, v14
	s_nop 1
	v_mov_b32_dpp v14, v0 row_mirror row_mask:0xf bank_mask:0xf
	s_and_saveexec_b64 s[2:3], s[36:37]
	s_cbranch_execz .LBB0_463
	v_mov_b32_e32 v67, v1
	s_waitcnt lgkmcnt(0)
	v_add_f32_e32 v0, v0, v14
	v_lshl_add_u64 v[14:15], v[4:5], 0, v[66:67]
	global_atomic_add_f32 v[14:15], v0, off offset:176
; DI float bflo(unsigned v) { return __uint_as_float(v << 16); }
; DI float bfhi(unsigned v) { return __uint_as_float(v & 0xffff0000u); }
; template <int EPI>
; DI void gemm_tile(const Params& p, int layer, int mt, int nt, u16* sm, int wv) {
;     ...
;       for (int t = 0; t < 16; ++t) {
;         const int row = (lane >> 4) + 4 * t;
;         const f32x4 a4 = *(const f32x4*)(stg + row * 68 + kc * 4);
;         const float v0 = bflo(xb[t][0]) + a4[0], v1 = bfhi(xb[t][0]) + a4[1], v2 = bflo(xb[t][1]) + a4[2], v3 = bfhi(xb[t][1]) + a4[3];
;         float sq = v0 * v0 + v1 * v1 + v2 * v2 + v3 * v3;
;         u32x2 pv = {pk2(v0, v1), pk2(v2, v3)};
;         if (has_next) *(u32x2*)(xrow + (size_t)row * DM) = pv;
;         else *(u32x2*)(x2row + (size_t)row * DM) = pv;
;         sq += shx(sq, lane, 1); sq += shx(sq, lane, 2); sq += shx(sq, lane, 4); sq += shx(sq, lane, 8);
;         if (kc == 0) atomicAdd(ssn + mrow0 + row, sq);
.LBB0_463:
	s_or_b64 exec, exec, s[2:3]
	s_waitcnt lgkmcnt(0)
	ds_read_b128 v[14:17], v69 offset:13056
	s_waitcnt vmcnt(14)
	v_lshlrev_b32_e32 v18, 16, v12
	v_and_b32_e32 v19, 0xffff0000, v12
	v_lshlrev_b32_e32 v12, 16, v13
	v_and_b32_e32 v13, 0xffff0000, v13
	s_waitcnt lgkmcnt(0)
	v_pk_add_f32 v[14:15], v[14:15], v[18:19]
	v_pk_add_f32 v[12:13], v[16:17], v[12:13]
	v_pk_mul_f32 v[16:17], v[14:15], v[14:15]
	v_pk_mul_f32 v[18:19], v[12:13], v[12:13]
	v_add_f32_e32 v16, v16, v17
	v_lshlrev_b32_e32 v0, 10, v108
	v_add_f32_e32 v16, v18, v16
	v_add_f32_e32 v16, v19, v16
	v_lshlrev_b32_e32 v0, 1, v0
	v_cvt_pk_bf16_f32 v14, v14, v15
	v_cvt_pk_bf16_f32 v15, v12, v13
	v_lshl_add_u64 v[12:13], v[10:11], 0, v[0:1]
	s_nop 1
	v_mov_b32_dpp v0, v16 quad_perm:[1,0,3,2] row_mask:0xf bank_mask:0xf
	global_store_dwordx2 v[12:13], v[14:15], off
	s_waitcnt lgkmcnt(0)
	v_add_f32_e32 v0, v16, v0
	s_nop 1
	v_mov_b32_dpp v12, v0 quad_perm:[2,3,0,1] row_mask:0xf bank_mask:0xf
	s_waitcnt lgkmcnt(0)
	v_add_f32_e32 v0, v0, v12
	s_nop 1
	v_mov_b32_dpp v12, v0 row_half_mirror row_mask:0xf bank_mask:0xf
	s_waitcnt lgkmcnt(0)
	v_add_f32_e32 v0, v0, v12
	s_nop 1
	v_mov_b32_dpp v12, v0 row_mirror row_mask:0xf bank_mask:0xf
	s_and_saveexec_b64 s[2:3], s[36:37]
	s_cbranch_execz .LBB0_465
	v_mov_b32_e32 v67, v1
	s_waitcnt lgkmcnt(0)
	v_add_f32_e32 v0, v0, v12
	v_lshl_add_u64 v[12:13], v[4:5], 0, v[66:67]
	global_atomic_add_f32 v[12:13], v0, off offset:192
.LBB0_465:
	s_or_b64 exec, exec, s[2:3]
	s_waitcnt lgkmcnt(0)
	ds_read_b128 v[12:15], v69 offset:14144
	s_waitcnt vmcnt(14)
	v_lshlrev_b32_e32 v16, 16, v8
	v_and_b32_e32 v17, 0xffff0000, v8
	v_lshlrev_b32_e32 v8, 16, v9
	v_and_b32_e32 v9, 0xffff0000, v9
	s_waitcnt lgkmcnt(0)
	v_pk_add_f32 v[12:13], v[12:13], v[16:17]
	v_pk_add_f32 v[8:9], v[14:15], v[8:9]
	v_pk_mul_f32 v[14:15], v[12:13], v[12:13]
	v_pk_mul_f32 v[16:17], v[8:9], v[8:9]
	v_add_f32_e32 v14, v14, v15
	v_lshlrev_b32_e32 v0, 10, v106
	v_add_f32_e32 v14, v16, v14
	v_add_f32_e32 v14, v17, v14
	v_lshlrev_b32_e32 v0, 1, v0
	v_cvt_pk_bf16_f32 v12, v12, v13
	v_cvt_pk_bf16_f32 v13, v8, v9
	v_lshl_add_u64 v[8:9], v[10:11], 0, v[0:1]
	s_nop 1
	v_mov_b32_dpp v0, v14 quad_perm:[1,0,3,2] row_mask:0xf bank_mask:0xf
	global_store_dwordx2 v[8:9], v[12:13], off
	s_waitcnt lgkmcnt(0)
	v_add_f32_e32 v0, v14, v0
	s_nop 1
	v_mov_b32_dpp v8, v0 quad_perm:[2,3,0,1] row_mask:0xf bank_mask:0xf
	s_waitcnt lgkmcnt(0)
	v_add_f32_e32 v0, v0, v8
	s_nop 1
	v_mov_b32_dpp v8, v0 row_half_mirror row_mask:0xf bank_mask:0xf
	s_waitcnt lgkmcnt(0)
	v_add_f32_e32 v0, v0, v8
	s_nop 1
	v_mov_b32_dpp v8, v0 row_mirror row_mask:0xf bank_mask:0xf
	s_and_saveexec_b64 s[2:3], s[36:37]
	s_cbranch_execz .LBB0_467
	v_mov_b32_e32 v67, v1
	s_waitcnt lgkmcnt(0)
	v_add_f32_e32 v0, v0, v8
	v_lshl_add_u64 v[8:9], v[4:5], 0, v[66:67]
	global_atomic_add_f32 v[8:9], v0, off offset:208
.LBB0_467:
	s_or_b64 exec, exec, s[2:3]
	ds_read_b128 v[12:15], v69 offset:15232
	s_waitcnt vmcnt(14) lgkmcnt(1)
	v_lshlrev_b32_e32 v8, 16, v6
	v_and_b32_e32 v9, 0xffff0000, v6
	v_lshlrev_b32_e32 v6, 16, v7
	v_and_b32_e32 v7, 0xffff0000, v7
	s_waitcnt lgkmcnt(0)
	v_pk_add_f32 v[8:9], v[12:13], v[8:9]
	v_pk_add_f32 v[6:7], v[14:15], v[6:7]
	v_pk_mul_f32 v[12:13], v[8:9], v[8:9]
	v_pk_mul_f32 v[14:15], v[6:7], v[6:7]
	v_add_f32_e32 v12, v12, v13
	v_lshlrev_b32_e32 v0, 10, v103
	v_add_f32_e32 v12, v14, v12
	v_add_f32_e32 v12, v15, v12
	v_lshlrev_b32_e32 v0, 1, v0
	v_cvt_pk_bf16_f32 v8, v8, v9
	v_cvt_pk_bf16_f32 v9, v6, v7
	v_lshl_add_u64 v[6:7], v[10:11], 0, v[0:1]
	s_nop 1
	v_mov_b32_dpp v0, v12 quad_perm:[1,0,3,2] row_mask:0xf bank_mask:0xf
	global_store_dwordx2 v[6:7], v[8:9], off
	s_waitcnt lgkmcnt(0)
	v_add_f32_e32 v0, v12, v0
	s_nop 1
	v_mov_b32_dpp v6, v0 quad_perm:[2,3,0,1] row_mask:0xf bank_mask:0xf
	s_waitcnt lgkmcnt(0)
	v_add_f32_e32 v0, v0, v6
	s_nop 1
	v_mov_b32_dpp v6, v0 row_half_mirror row_mask:0xf bank_mask:0xf
	s_waitcnt lgkmcnt(0)
	v_add_f32_e32 v0, v0, v6
	s_nop 1
	v_mov_b32_dpp v6, v0 row_mirror row_mask:0xf bank_mask:0xf
	s_and_saveexec_b64 s[2:3], s[36:37]
	s_cbranch_execz .LBB0_469
	v_mov_b32_e32 v67, v1
	s_waitcnt lgkmcnt(0)
	v_add_f32_e32 v0, v0, v6
	v_lshl_add_u64 v[6:7], v[4:5], 0, v[66:67]
	global_atomic_add_f32 v[6:7], v0, off offset:224
.LBB0_469:
	s_or_b64 exec, exec, s[2:3]
	s_waitcnt lgkmcnt(0)
	ds_read_b128 v[6:9], v69 offset:16320
	s_waitcnt vmcnt(14)
	v_lshlrev_b32_e32 v12, 16, v2
	v_and_b32_e32 v13, 0xffff0000, v2
	v_lshlrev_b32_e32 v2, 16, v3
	v_and_b32_e32 v3, 0xffff0000, v3
	s_waitcnt lgkmcnt(0)
	v_pk_add_f32 v[6:7], v[6:7], v[12:13]
	v_pk_add_f32 v[2:3], v[8:9], v[2:3]
	v_pk_mul_f32 v[8:9], v[6:7], v[6:7]
	v_pk_mul_f32 v[12:13], v[2:3], v[2:3]
	v_add_f32_e32 v8, v8, v9
	v_lshlrev_b32_e32 v0, 10, v102
	v_add_f32_e32 v8, v12, v8
	v_add_f32_e32 v8, v13, v8
	v_lshlrev_b32_e32 v0, 1, v0
	v_cvt_pk_bf16_f32 v6, v6, v7
	v_cvt_pk_bf16_f32 v7, v2, v3
	v_lshl_add_u64 v[2:3], v[10:11], 0, v[0:1]
	s_nop 1
	v_mov_b32_dpp v0, v8 quad_perm:[1,0,3,2] row_mask:0xf bank_mask:0xf
	global_store_dwordx2 v[2:3], v[6:7], off
	s_waitcnt lgkmcnt(0)
	v_add_f32_e32 v0, v8, v0
	s_nop 1
	v_mov_b32_dpp v2, v0 quad_perm:[2,3,0,1] row_mask:0xf bank_mask:0xf
	s_waitcnt lgkmcnt(0)
	v_add_f32_e32 v0, v0, v2
	s_nop 1
	v_mov_b32_dpp v2, v0 row_half_mirror row_mask:0xf bank_mask:0xf
	s_waitcnt lgkmcnt(0)
	v_add_f32_e32 v0, v0, v2
	s_nop 1
	v_mov_b32_dpp v2, v0 row_mirror row_mask:0xf bank_mask:0xf
	s_and_saveexec_b64 s[2:3], s[36:37]
	s_cbranch_execz .LBB0_394
	v_mov_b32_e32 v67, v1
	s_waitcnt lgkmcnt(0)
	v_add_f32_e32 v0, v0, v2
	v_lshl_add_u64 v[2:3], v[4:5], 0, v[66:67]
	global_atomic_add_f32 v[2:3], v0, off offset:240
	s_branch .LBB0_394
